# attention output epilogues (MLA and cross-attention): half-wave chunk pairs exchanged with v_permlane32_swap, 16-byte stores instead of twice as many 8-byte stores
# speedup vs baseline: 1.0011x; 1.0011x over previous
.Lmla_fin_join:
	v_add_f32_e32 v34, 0, v82
	v_add_f32_e32 v34, v83, v34
	v_add_f32_e32 v34, v84, v34
	v_add_f32_e32 v34, v85, v34
	v_add_f32_e32 v34, v86, v34
	v_add_f32_e32 v34, v87, v34
	v_add_f32_e32 v34, v88, v34
	v_add_f32_e32 v34, v89, v34
	v_add_f32_e32 v34, v90, v34
	v_add_f32_e32 v34, v91, v34
	v_add_f32_e32 v34, v92, v34
	v_add_f32_e32 v34, v93, v34
	v_add_f32_e32 v34, v94, v34
	v_add_f32_e32 v34, v95, v34
	v_add_f32_e32 v34, v96, v34
	v_add_f32_e32 v34, v97, v34
	v_add_f32_e32 v34, v99, v34
	v_add_f32_e32 v34, v100, v34
	v_add_f32_e32 v34, v101, v34
	v_add_f32_e32 v34, v102, v34
	v_add_f32_e32 v34, v103, v34
	v_add_f32_e32 v34, v104, v34
	v_add_f32_e32 v34, v105, v34
	v_add_f32_e32 v34, v106, v34
	v_add_f32_e32 v34, v74, v34
	v_add_f32_e32 v34, v75, v34
	v_add_f32_e32 v34, v76, v34
	v_add_f32_e32 v34, v77, v34
	v_add_f32_e32 v34, v78, v34
	v_add_f32_e32 v34, v79, v34
	v_add_f32_e32 v34, v80, v34
	v_add_f32_e32 v34, v81, v34
	v_add_f32_e32 v34, v107, v34
	v_add_f32_e32 v34, v108, v34
	v_add_f32_e32 v34, v110, v34
	v_add_f32_e32 v34, v111, v34
	v_add_f32_e32 v34, v113, v34
	v_add_f32_e32 v34, v114, v34
	v_add_f32_e32 v34, v70, v34
	v_add_f32_e32 v34, v71, v34
	v_add_f32_e32 v34, v72, v34
	v_add_f32_e32 v34, v73, v34
	v_add_f32_e32 v34, v115, v34
	v_add_f32_e32 v34, v66, v34
	v_add_f32_e32 v34, v62, v34
	v_add_f32_e32 v34, v63, v34
	v_add_f32_e32 v34, v64, v34
	v_add_f32_e32 v34, v65, v34
	v_add_f32_e32 v34, v67, v34
	v_add_f32_e32 v34, v68, v34
	v_add_f32_e32 v34, v69, v34
	v_add_f32_e32 v34, v58, v34
	v_add_f32_e32 v34, v59, v34
	v_add_f32_e32 v34, v60, v34
	v_add_f32_e32 v34, v61, v34
	v_add_f32_e32 v34, v54, v34
	v_add_f32_e32 v34, v55, v34
	v_add_f32_e32 v34, v56, v34
	v_add_f32_e32 v34, v57, v34
	v_add_f32_e32 v34, v50, v34
	v_add_f32_e32 v34, v46, v34
	v_add_f32_e32 v34, v47, v34
	v_add_f32_e32 v34, v48, v34
	v_add_f32_e32 v34, v49, v34
	v_add_f32_e32 v1, v34, v1
	s_setprio 0
	ds_bpermute_b32 v36, v190, v1
	v_lshl_add_u64 v[34:35], s[10:11], 0, v[158:159]
	v_lshl_add_u64 v[34:35], v[34:35], 0, v[134:135]
	s_add_i32 s48, s48, s33
	s_cmpk_gt_i32 s48, 0x3ff
	s_waitcnt lgkmcnt(0)
	v_add_f32_e32 v1, v1, v36
	v_div_scale_f32 v36, s[10:11], v1, v1, 1.0
	v_rcp_f32_e32 v37, v36
	v_div_scale_f32 v38, vcc, 1.0, v1, 1.0
	v_fma_f32 v39, -v36, v37, 1.0
	v_fmac_f32_e32 v37, v39, v37
	v_mul_f32_e32 v39, v38, v37
	v_fma_f32 v40, -v36, v39, v38
	v_fmac_f32_e32 v39, v40, v37
	v_fma_f32 v36, -v36, v39, v38
	v_div_fmas_f32 v36, v36, v37, v39
	v_div_fixup_f32 v36, v36, v1, 1.0
	v_lshl_add_u64 v[34:35], v[34:35], 0, v[134:135]
	v_pk_mul_f32 v[18:19], v[18:19], v[36:37] op_sel_hi:[1,0]
	v_pk_mul_f32 v[20:21], v[20:21], v[36:37] op_sel_hi:[1,0]
	v_pk_mul_f32 v[22:23], v[22:23], v[36:37] op_sel_hi:[1,0]
	v_pk_mul_f32 v[24:25], v[24:25], v[36:37] op_sel_hi:[1,0]
	v_pk_mul_f32 v[26:27], v[26:27], v[36:37] op_sel_hi:[1,0]
	v_pk_mul_f32 v[28:29], v[28:29], v[36:37] op_sel_hi:[1,0]
	v_pk_mul_f32 v[30:31], v[30:31], v[36:37] op_sel_hi:[1,0]
	v_pk_mul_f32 v[32:33], v[32:33], v[36:37] op_sel_hi:[1,0]
	v_cvt_pk_bf16_f32 v18, v18, v19
	v_cvt_pk_bf16_f32 v19, v20, v21
	v_cvt_pk_bf16_f32 v20, v22, v23
	v_cvt_pk_bf16_f32 v21, v24, v25
	v_cvt_pk_bf16_f32 v22, v26, v27
	v_cvt_pk_bf16_f32 v23, v28, v29
	v_cvt_pk_bf16_f32 v24, v30, v31
	v_cvt_pk_bf16_f32 v25, v32, v33
	v_pk_mul_f32 v[2:3], v[2:3], v[36:37] op_sel_hi:[1,0]
	v_pk_mul_f32 v[4:5], v[4:5], v[36:37] op_sel_hi:[1,0]
	v_pk_mul_f32 v[6:7], v[6:7], v[36:37] op_sel_hi:[1,0]
	v_pk_mul_f32 v[8:9], v[8:9], v[36:37] op_sel_hi:[1,0]
	v_pk_mul_f32 v[10:11], v[10:11], v[36:37] op_sel_hi:[1,0]
	v_pk_mul_f32 v[12:13], v[12:13], v[36:37] op_sel_hi:[1,0]
	v_pk_mul_f32 v[14:15], v[14:15], v[36:37] op_sel_hi:[1,0]
	v_pk_mul_f32 v[16:17], v[16:17], v[36:37] op_sel_hi:[1,0]
	v_cvt_pk_bf16_f32 v2, v2, v3
	v_cvt_pk_bf16_f32 v3, v4, v5
	v_cvt_pk_bf16_f32 v4, v6, v7
	v_cvt_pk_bf16_f32 v5, v8, v9
	v_cvt_pk_bf16_f32 v6, v10, v11
	v_cvt_pk_bf16_f32 v7, v12, v13
	v_cvt_pk_bf16_f32 v8, v14, v15
	v_cvt_pk_bf16_f32 v9, v16, v17
	s_nop 1
	v_permlane32_swap_b32_e32 v18, v20
	v_permlane32_swap_b32_e32 v19, v21
	v_permlane32_swap_b32_e32 v22, v24
	v_permlane32_swap_b32_e32 v23, v25
	v_permlane32_swap_b32_e32 v2, v4
	v_permlane32_swap_b32_e32 v3, v5
	v_permlane32_swap_b32_e32 v6, v8
	v_permlane32_swap_b32_e32 v7, v9
	global_store_dwordx4 v[34:35], v[18:21], off
	global_store_dwordx4 v[34:35], v[22:25], off offset:32
	global_store_dwordx4 v[34:35], v[2:5], off offset:64
	global_store_dwordx4 v[34:35], v[6:9], off offset:96
	s_cbranch_scc1 .LBB0_828

.Lxa_join:
	ds_bpermute_b32 v66, v139, v178
	v_mov_b32_e32 v139, v135
	s_add_i32 s12, s12, s3
	s_sub_i32 s14, s14, s3
	s_cmpk_gt_i32 s12, 0x3ff
	s_waitcnt lgkmcnt(0)
	v_add_f32_e32 v68, v178, v66
	v_div_scale_f32 v69, s[8:9], v68, v68, 1.0
	v_rcp_f32_e32 v70, v69
	v_div_scale_f32 v71, vcc, 1.0, v68, 1.0
	v_lshl_add_u64 v[66:67], v[136:137], 0, v[138:139]
	v_fma_f32 v72, -v69, v70, 1.0
	v_fmac_f32_e32 v70, v72, v70
	v_mul_f32_e32 v72, v71, v70
	v_fma_f32 v73, -v69, v72, v71
	v_fmac_f32_e32 v72, v73, v70
	v_fma_f32 v69, -v69, v72, v71
	v_div_fmas_f32 v69, v69, v70, v72
	v_div_fixup_f32 v68, v69, v68, 1.0
	v_lshl_add_u64 v[66:67], v[66:67], 0, v[138:139]
	v_pk_mul_f32 v[50:51], v[50:51], v[68:69] op_sel_hi:[1,0]
	v_pk_mul_f32 v[52:53], v[52:53], v[68:69] op_sel_hi:[1,0]
	v_pk_mul_f32 v[54:55], v[54:55], v[68:69] op_sel_hi:[1,0]
	v_pk_mul_f32 v[56:57], v[56:57], v[68:69] op_sel_hi:[1,0]
	v_pk_mul_f32 v[58:59], v[58:59], v[68:69] op_sel_hi:[1,0]
	v_pk_mul_f32 v[60:61], v[60:61], v[68:69] op_sel_hi:[1,0]
	v_pk_mul_f32 v[62:63], v[62:63], v[68:69] op_sel_hi:[1,0]
	v_pk_mul_f32 v[64:65], v[64:65], v[68:69] op_sel_hi:[1,0]
	v_cvt_pk_bf16_f32 v50, v50, v51
	v_cvt_pk_bf16_f32 v51, v52, v53
	v_cvt_pk_bf16_f32 v52, v54, v55
	v_cvt_pk_bf16_f32 v53, v56, v57
	v_cvt_pk_bf16_f32 v54, v58, v59
	v_cvt_pk_bf16_f32 v55, v60, v61
	v_cvt_pk_bf16_f32 v56, v62, v63
	v_cvt_pk_bf16_f32 v57, v64, v65
	v_pk_mul_f32 v[34:35], v[34:35], v[68:69] op_sel_hi:[1,0]
	v_pk_mul_f32 v[36:37], v[36:37], v[68:69] op_sel_hi:[1,0]
	v_pk_mul_f32 v[38:39], v[38:39], v[68:69] op_sel_hi:[1,0]
	v_pk_mul_f32 v[40:41], v[40:41], v[68:69] op_sel_hi:[1,0]
	v_pk_mul_f32 v[42:43], v[42:43], v[68:69] op_sel_hi:[1,0]
	v_pk_mul_f32 v[44:45], v[44:45], v[68:69] op_sel_hi:[1,0]
	v_pk_mul_f32 v[46:47], v[46:47], v[68:69] op_sel_hi:[1,0]
	v_pk_mul_f32 v[48:49], v[48:49], v[68:69] op_sel_hi:[1,0]
	v_cvt_pk_bf16_f32 v34, v34, v35
	v_cvt_pk_bf16_f32 v35, v36, v37
	v_cvt_pk_bf16_f32 v36, v38, v39
	v_cvt_pk_bf16_f32 v37, v40, v41
	v_cvt_pk_bf16_f32 v38, v42, v43
	v_cvt_pk_bf16_f32 v39, v44, v45
	v_cvt_pk_bf16_f32 v40, v46, v47
	v_cvt_pk_bf16_f32 v41, v48, v49
	v_pk_mul_f32 v[18:19], v[18:19], v[68:69] op_sel_hi:[1,0]
	v_pk_mul_f32 v[20:21], v[20:21], v[68:69] op_sel_hi:[1,0]
	v_pk_mul_f32 v[22:23], v[22:23], v[68:69] op_sel_hi:[1,0]
	v_pk_mul_f32 v[24:25], v[24:25], v[68:69] op_sel_hi:[1,0]
	v_pk_mul_f32 v[26:27], v[26:27], v[68:69] op_sel_hi:[1,0]
	v_pk_mul_f32 v[28:29], v[28:29], v[68:69] op_sel_hi:[1,0]
	v_pk_mul_f32 v[30:31], v[30:31], v[68:69] op_sel_hi:[1,0]
	v_pk_mul_f32 v[32:33], v[32:33], v[68:69] op_sel_hi:[1,0]
	v_cvt_pk_bf16_f32 v18, v18, v19
	v_cvt_pk_bf16_f32 v19, v20, v21
	v_cvt_pk_bf16_f32 v20, v22, v23
	v_cvt_pk_bf16_f32 v21, v24, v25
	v_cvt_pk_bf16_f32 v22, v26, v27
	v_cvt_pk_bf16_f32 v23, v28, v29
	v_cvt_pk_bf16_f32 v24, v30, v31
	v_cvt_pk_bf16_f32 v25, v32, v33
	v_pk_mul_f32 v[2:3], v[2:3], v[68:69] op_sel_hi:[1,0]
	v_pk_mul_f32 v[4:5], v[4:5], v[68:69] op_sel_hi:[1,0]
	v_pk_mul_f32 v[6:7], v[6:7], v[68:69] op_sel_hi:[1,0]
	v_pk_mul_f32 v[8:9], v[8:9], v[68:69] op_sel_hi:[1,0]
	v_pk_mul_f32 v[10:11], v[10:11], v[68:69] op_sel_hi:[1,0]
	v_pk_mul_f32 v[12:13], v[12:13], v[68:69] op_sel_hi:[1,0]
	v_pk_mul_f32 v[14:15], v[14:15], v[68:69] op_sel_hi:[1,0]
	v_pk_mul_f32 v[16:17], v[16:17], v[68:69] op_sel_hi:[1,0]
	v_cvt_pk_bf16_f32 v2, v2, v3
	v_cvt_pk_bf16_f32 v3, v4, v5
	v_cvt_pk_bf16_f32 v4, v6, v7
	v_cvt_pk_bf16_f32 v5, v8, v9
	v_cvt_pk_bf16_f32 v6, v10, v11
	v_cvt_pk_bf16_f32 v7, v12, v13
	v_cvt_pk_bf16_f32 v8, v14, v15
	v_cvt_pk_bf16_f32 v9, v16, v17
	s_nop 1
	v_permlane32_swap_b32_e32 v50, v52
	v_permlane32_swap_b32_e32 v51, v53
	v_permlane32_swap_b32_e32 v54, v56
	v_permlane32_swap_b32_e32 v55, v57
	v_permlane32_swap_b32_e32 v34, v36
	v_permlane32_swap_b32_e32 v35, v37
	v_permlane32_swap_b32_e32 v38, v40
	v_permlane32_swap_b32_e32 v39, v41
	v_permlane32_swap_b32_e32 v18, v20
	v_permlane32_swap_b32_e32 v19, v21
	v_permlane32_swap_b32_e32 v22, v24
	v_permlane32_swap_b32_e32 v23, v25
	v_permlane32_swap_b32_e32 v2, v4
	v_permlane32_swap_b32_e32 v3, v5
	v_permlane32_swap_b32_e32 v6, v8
	v_permlane32_swap_b32_e32 v7, v9
	global_store_dwordx4 v[66:67], v[50:53], off
	global_store_dwordx4 v[66:67], v[54:57], off offset:32
	global_store_dwordx4 v[66:67], v[34:37], off offset:64
	global_store_dwordx4 v[66:67], v[38:41], off offset:96
	global_store_dwordx4 v[66:67], v[18:21], off offset:128
	global_store_dwordx4 v[66:67], v[22:25], off offset:160
	global_store_dwordx4 v[66:67], v[2:5], off offset:192
	global_store_dwordx4 v[66:67], v[6:9], off offset:224
	s_cbranch_scc0 .LBB0_830
